# v22 + gate/up epilogue (prompt units): the conv's row t-1/t-2 lane fetches use DPP row rotates instead of ds_bpermute through LDS (128 per unit)
# speedup vs baseline: 1.0090x; 1.0090x over previous
; #define PG8_LAS __attribute__((address_space(3)))
; __device__ __forceinline__ unsigned cvt_pk_bf16(float lo, float hi) { f32x2_t v = {lo, hi}; bf16x2_t b = __builtin_convertvector(v, bf16x2_t); return __builtin_bit_cast(unsigned, b); }
; __device__ __forceinline__ float sigm(float x) { return __builtin_amdgcn_rcpf(1.0f + __builtin_amdgcn_exp2f(-x * LOG2E)); }
;     __device__ __forceinline__ void operator()(const f32x4 (&acc)[2][2][4][2], const Unit& u, int wr, int wc, int fr, int fq) const {
;     ...
;             asm volatile("s_waitcnt lgkmcnt(0)" ::: "memory"); __builtin_amdgcn_s_barrier(); asm volatile("" ::: "memory");
; #pragma unroll
;             for (int n = 0; n < 2; ++n) {
;                 const f32x4 w0 = *(const f32x4*)(cw + colt + 4 * n), w1 = *(const f32x4*)(cw + 2816 + colt + 4 * n), w2 = *(const f32x4*)(cw + 5632 + colt + 4 * n), bb = *(const f32x4*)(cb + colt + 4 * n);
; #pragma unroll
;                 for (int ai = 0; ai < 2; ++ai) {
;                     f32x4 prevA = {0.f, 0.f, 0.f, 0.f};
;                     const bool has_prev = (wr == 1) || (ai == 1);
;     ...
;                     if (has_prev && fr >= 14) { const int pw = (wr == 1 ? 0 : 4) + wc, pai = (wr == 1) ? ai : 0; prevA = *(const PG8_LAS f32x4*)(xch + ((pw * 8 + (fr - 14) * 4 + fq) * 16 + pai * 8 + n * 4)); }
;     ...
; #pragma unroll
;                     for (int m = 0; m < 4; ++m) {
;                         const int row = row0 + ai * HALF + m * 16;
;                         const f32x4 a = acc[ai][0][m][n] * rs[ai][m], uu = acc[ai][1][m][n] * rs[ai][m]; f32x4 gg;
; #pragma unroll
;                         for (int j = 0; j < 4; ++j) {
;                             const float p1 = __builtin_bit_cast(float, __builtin_amdgcn_ds_bpermute(idx1, __builtin_bit_cast(int, fr == 15 ? prevA[j] : a[j])));
;                             const float p2 = __builtin_bit_cast(float, __builtin_amdgcn_ds_bpermute(idx2, __builtin_bit_cast(int, fr >= 14 ? prevA[j] : a[j])));
;                             const float c = bb[j] + w0[j] * p2 + w1[j] * p1 + w2[j] * a[j];
;                             gg[j] = c * sigm(c) * uu[j];
;                         }
;                         *(u32x2*)(G + (size_t)row * 2816 + colt + 4 * n) = (u32x2){cvt_pk_bf16(gg[0], gg[1]), cvt_pk_bf16(gg[2], gg[3])};
.LBB0_998:
	s_or_b64 exec, exec, s[8:9]
	s_waitcnt lgkmcnt(0)
	s_barrier
	s_load_dwordx4 s[20:23], s[14:15], 0x98
	v_lshlrev_b64 v[194:195], 2, v[168:169]
	v_lshl_add_u64 v[134:135], s[72:73], 0, v[194:195]
	v_lshl_add_u64 v[138:139], s[74:75], 0, v[194:195]
	v_readlane_b32 s8, v255, 25
	s_waitcnt lgkmcnt(0)
	v_lshl_add_u64 v[196:197], s[20:21], 0, v[194:195]
	v_lshl_add_u64 v[198:199], s[22:23], 0, v[194:195]
	global_load_dwordx4 v[130:133], v[196:197], off
	s_nop 0
	global_load_dwordx4 v[134:137], v[134:135], off
	s_nop 0
	global_load_dwordx4 v[138:141], v[138:139], off
	v_lshlrev_b32_e32 v171, 6, v239
	global_load_dwordx4 v[142:145], v[198:199], off
	v_add_co_u32_e32 v248, vcc, 0x2000, v196
	global_load_dwordx4 v[218:221], v[196:197], off offset:16
	s_nop 0
	v_addc_co_u32_e32 v249, vcc, 0, v197, vcc
	v_add_co_u32_e32 v250, vcc, 0x5000, v196
	s_nop 1
	v_addc_co_u32_e32 v251, vcc, 0, v197, vcc
	global_load_dwordx4 v[222:225], v[248:249], off offset:3088
	global_load_dwordx4 v[226:229], v[250:251], off offset:2064
	global_load_dwordx4 v[244:247], v[198:199], off offset:16
	s_and_b64 s[12:13], s[40:41], s[6:7]
	v_mov_b32_e32 v154, 0
	v_add_u32_e32 v173, s8, v146
	v_mov_b32_e32 v155, 0
	v_mov_b32_e32 v156, 0
	v_mov_b32_e32 v157, 0
	s_and_saveexec_b64 s[8:9], s[12:13]
	s_movk_i32 s20, 0xf200
	v_add3_u32 v146, v173, v171, s20
	ds_read_b128 v[154:157], v146
	s_or_b64 exec, exec, s[8:9]
	v_cmp_eq_u32_e32 vcc, 0, v237
	v_cmp_eq_u32_e64 s[8:9], 15, v237
	v_pk_mul_f32 v[148:149], v[128:129], v[184:185] op_sel_hi:[1,0]
	v_cndmask_b32_e64 v146, -1, 15, vcc
	v_cmp_gt_u32_e32 vcc, 2, v237
	v_add_lshl_u32 v209, v146, v238, 2
	v_pk_mul_f32 v[152:153], v[96:97], v[184:185] op_sel_hi:[1,0]
	v_cndmask_b32_e64 v146, -2, 14, vcc
	v_add_lshl_u32 v208, v146, v238, 2
	v_pk_mul_f32 v[146:147], v[126:127], v[184:185] op_sel_hi:[1,0]
	v_pk_mul_f32 v[150:151], v[94:95], v[184:185] op_sel_hi:[1,0]
	s_waitcnt lgkmcnt(0)
	v_cndmask_b32_e64 v175, v146, v154, s[8:9]
	s_nop 1
	v_mov_b32_dpp v200, v175 row_ror:1 row_mask:0xf bank_mask:0xf
	v_cndmask_b32_e64 v154, v146, v154, s[6:7]
	v_cndmask_b32_e64 v175, v147, v155, s[8:9]
	v_cndmask_b32_e64 v155, v147, v155, s[6:7]
	v_mov_b32_dpp v154, v154 row_ror:2 row_mask:0xf bank_mask:0xf
	s_nop 1
	v_mov_b32_dpp v155, v155 row_ror:2 row_mask:0xf bank_mask:0xf
	v_mov_b32_dpp v201, v175 row_ror:1 row_mask:0xf bank_mask:0xf
	s_and_b64 s[88:89], s[70:71], vcc
	s_waitcnt vmcnt(0) lgkmcnt(1)
	v_pk_fma_f32 v[154:155], v[130:131], v[154:155], v[142:143]
	s_waitcnt lgkmcnt(0)
	v_pk_fma_f32 v[154:155], v[134:135], v[200:201], v[154:155]
	s_nop 0
	v_pk_fma_f32 v[154:155], v[146:147], v[138:139], v[154:155]
	s_nop 0
	v_mul_f32_e32 v175, 0xbfb8aa3b, v154
	v_exp_f32_e32 v175, v175
	s_nop 0
	v_add_f32_e32 v175, 1.0, v175
	v_rcp_f32_e32 v200, v175
	v_mul_f32_e32 v175, 0xbfb8aa3b, v155
	v_exp_f32_e32 v175, v175
	s_nop 0
	v_add_f32_e32 v175, 1.0, v175
	v_rcp_f32_e32 v201, v175
	v_cndmask_b32_e64 v175, v148, v156, s[8:9]
	v_cndmask_b32_e64 v156, v148, v156, s[6:7]
	s_nop 1
	v_mov_b32_dpp v156, v156 row_ror:2 row_mask:0xf bank_mask:0xf
	v_pk_mul_f32 v[154:155], v[154:155], v[200:201]
	v_mov_b32_dpp v200, v175 row_ror:1 row_mask:0xf bank_mask:0xf
	v_cndmask_b32_e64 v175, v149, v157, s[8:9]
	v_cndmask_b32_e64 v157, v149, v157, s[6:7]
	s_nop 1
	v_mov_b32_dpp v157, v157 row_ror:2 row_mask:0xf bank_mask:0xf
	v_mov_b32_dpp v201, v175 row_ror:1 row_mask:0xf bank_mask:0xf
	v_pk_mul_f32 v[154:155], v[150:151], v[154:155]
	s_waitcnt lgkmcnt(1)
	v_pk_fma_f32 v[156:157], v[132:133], v[156:157], v[144:145]
	s_waitcnt lgkmcnt(0)
	v_pk_fma_f32 v[156:157], v[136:137], v[200:201], v[156:157]
	v_cvt_pk_bf16_f32 v154, v154, v155
	v_pk_fma_f32 v[156:157], v[148:149], v[140:141], v[156:157]
	s_nop 0
	v_mul_f32_e32 v175, 0xbfb8aa3b, v156
	v_exp_f32_e32 v175, v175
	s_nop 0
	v_add_f32_e32 v175, 1.0, v175
	v_rcp_f32_e32 v200, v175
	v_mul_f32_e32 v175, 0xbfb8aa3b, v157
	v_exp_f32_e32 v175, v175
	s_nop 0
	v_add_f32_e32 v175, 1.0, v175
	v_rcp_f32_e32 v201, v175
	v_lshl_or_b32 v175, s34, 1, v237
	v_pk_mul_f32 v[156:157], v[156:157], v[200:201]
	s_nop 0
	v_pk_mul_f32 v[156:157], v[152:153], v[156:157]
	s_nop 0
	v_cvt_pk_bf16_f32 v155, v156, v157
	v_mov_b64_e32 v[156:157], s[42:43]
	v_mad_i64_i32 v[156:157], s[20:21], v192, s47, v[156:157]
	v_lshl_add_u64 v[206:207], v[168:169], 1, v[156:157]
	global_store_dwordx2 v[206:207], v[154:155], off
	s_and_saveexec_b64 s[90:91], s[88:89]
	s_cbranch_execz .LBB0_1002
	v_readlane_b32 s20, v255, 16
	v_readlane_b32 s21, v255, 17
	s_nop 1
	v_mov_b64_e32 v[154:155], s[20:21]
	v_mad_i64_i32 v[154:155], s[20:21], v175, s48, v[154:155]
	v_readlane_b32 s20, v255, 18
	v_lshl_add_u64 v[154:155], v[154:155], 0, v[194:195]
	v_readlane_b32 s21, v255, 19
	global_store_dwordx4 v[154:155], v[146:149], off
	s_nop 0
	v_mov_b64_e32 v[154:155], s[20:21]
	v_mad_i64_i32 v[154:155], s[20:21], v175, s48, v[154:155]
	v_lshl_add_u64 v[154:155], v[154:155], 0, v[194:195]
	global_store_dwordx4 v[154:155], v[150:153], off
; __device__ __forceinline__ unsigned cvt_pk_bf16(float lo, float hi) { f32x2_t v = {lo, hi}; bf16x2_t b = __builtin_convertvector(v, bf16x2_t); return __builtin_bit_cast(unsigned, b); }
; __device__ __forceinline__ float sigm(float x) { return __builtin_amdgcn_rcpf(1.0f + __builtin_amdgcn_exp2f(-x * LOG2E)); }
;     __device__ __forceinline__ void operator()(const f32x4 (&acc)[2][2][4][2], const Unit& u, int wr, int wc, int fr, int fq) const {
;     ...
;                     for (int m = 0; m < 4; ++m) {
;                         const int row = row0 + ai * HALF + m * 16;
;                         const f32x4 a = acc[ai][0][m][n] * rs[ai][m], uu = acc[ai][1][m][n] * rs[ai][m]; f32x4 gg;
; #pragma unroll
;                         for (int j = 0; j < 4; ++j) {
;                             const float p1 = __builtin_bit_cast(float, __builtin_amdgcn_ds_bpermute(idx1, __builtin_bit_cast(int, fr == 15 ? prevA[j] : a[j])));
;                             const float p2 = __builtin_bit_cast(float, __builtin_amdgcn_ds_bpermute(idx2, __builtin_bit_cast(int, fr >= 14 ? prevA[j] : a[j])));
;                             const float c = bb[j] + w0[j] * p2 + w1[j] * p1 + w2[j] * a[j];
;                             gg[j] = c * sigm(c) * uu[j];
;                         }
;                         *(u32x2*)(G + (size_t)row * 2816 + colt + 4 * n) = (u32x2){cvt_pk_bf16(gg[0], gg[1]), cvt_pk_bf16(gg[2], gg[3])};
.LBB0_1002:
	s_or_b64 exec, exec, s[90:91]
	v_pk_mul_f32 v[154:155], v[118:119], v[182:183] op_sel_hi:[1,0]
	v_pk_mul_f32 v[152:153], v[120:121], v[182:183] op_sel_hi:[1,0]
	v_cndmask_b32_e64 v177, v154, v146, s[8:9]
	s_nop 1
	v_mov_b32_dpp v200, v177 row_ror:1 row_mask:0xf bank_mask:0xf
	v_cndmask_b32_e64 v146, v154, v146, s[6:7]
	v_cndmask_b32_e64 v177, v155, v147, s[8:9]
	v_cndmask_b32_e64 v147, v155, v147, s[6:7]
	v_mov_b32_dpp v146, v146 row_ror:2 row_mask:0xf bank_mask:0xf
	s_nop 1
	v_mov_b32_dpp v147, v147 row_ror:2 row_mask:0xf bank_mask:0xf
	v_mov_b32_dpp v201, v177 row_ror:1 row_mask:0xf bank_mask:0xf
	v_pk_mul_f32 v[156:157], v[86:87], v[182:183] op_sel_hi:[1,0]
	v_pk_mul_f32 v[150:151], v[88:89], v[182:183] op_sel_hi:[1,0]
	v_pk_mul_f32 v[204:205], v[78:79], v[180:181] op_sel_hi:[1,0]
	s_waitcnt lgkmcnt(1)
	v_pk_fma_f32 v[146:147], v[130:131], v[146:147], v[142:143]
	v_pk_mul_f32 v[202:203], v[80:81], v[180:181] op_sel_hi:[1,0]
	s_waitcnt lgkmcnt(0)
	v_pk_fma_f32 v[146:147], v[134:135], v[200:201], v[146:147]
	s_nop 0
	v_pk_fma_f32 v[146:147], v[154:155], v[138:139], v[146:147]
	s_nop 0
	v_mul_f32_e32 v177, 0xbfb8aa3b, v146
	v_exp_f32_e32 v177, v177
	s_nop 0
	v_add_f32_e32 v177, 1.0, v177
	v_rcp_f32_e32 v200, v177
	v_mul_f32_e32 v177, 0xbfb8aa3b, v147
	v_exp_f32_e32 v177, v177
	s_nop 0
	v_add_f32_e32 v177, 1.0, v177
	v_rcp_f32_e32 v201, v177
	s_nop 0
	v_pk_mul_f32 v[146:147], v[146:147], v[200:201]
	s_nop 0
	v_pk_mul_f32 v[146:147], v[156:157], v[146:147]
	v_cndmask_b32_e64 v156, v152, v148, s[8:9]
	v_cndmask_b32_e64 v148, v152, v148, s[6:7]
	v_cndmask_b32_e64 v157, v153, v149, s[8:9]
	v_cndmask_b32_e64 v149, v153, v149, s[6:7]
	v_mov_b32_dpp v148, v148 row_ror:2 row_mask:0xf bank_mask:0xf
	s_nop 1
	v_mov_b32_dpp v149, v149 row_ror:2 row_mask:0xf bank_mask:0xf
	v_mov_b32_dpp v156, v156 row_ror:1 row_mask:0xf bank_mask:0xf
	v_mov_b32_dpp v157, v157 row_ror:1 row_mask:0xf bank_mask:0xf
	s_waitcnt lgkmcnt(2)
	v_pk_fma_f32 v[148:149], v[132:133], v[148:149], v[144:145]
	s_waitcnt lgkmcnt(0)
	v_pk_fma_f32 v[148:149], v[136:137], v[156:157], v[148:149]
	s_nop 0
	v_pk_fma_f32 v[148:149], v[152:153], v[140:141], v[148:149]
	s_nop 0
	v_mul_f32_e32 v156, 0xbfb8aa3b, v148
	v_mul_f32_e32 v157, 0xbfb8aa3b, v149
	v_exp_f32_e32 v156, v156
	v_exp_f32_e32 v157, v157
	v_add_f32_e32 v156, 1.0, v156
	v_add_f32_e32 v157, 1.0, v157
	v_rcp_f32_e32 v156, v156
	v_rcp_f32_e32 v157, v157
	s_nop 0
	v_pk_mul_f32 v[148:149], v[148:149], v[156:157]
	s_nop 0
	v_pk_mul_f32 v[148:149], v[150:151], v[148:149]
	v_cvt_pk_bf16_f32 v156, v146, v147
	v_mov_b64_e32 v[146:147], s[42:43]
	v_cvt_pk_bf16_f32 v157, v148, v149
	v_mad_i64_i32 v[148:149], s[20:21], v190, s47, v[146:147]
	v_lshlrev_b64 v[150:151], 1, v[168:169]
	v_lshl_add_u64 v[200:201], v[148:149], 0, v[150:151]
	global_store_dwordx2 v[200:201], v[156:157], off
	v_pk_mul_f32 v[156:157], v[110:111], v[180:181] op_sel_hi:[1,0]
	v_pk_mul_f32 v[148:149], v[112:113], v[180:181] op_sel_hi:[1,0]
	v_cndmask_b32_e64 v177, v156, v154, s[8:9]
	s_nop 1
	v_mov_b32_dpp v210, v177 row_ror:1 row_mask:0xf bank_mask:0xf
	v_cndmask_b32_e64 v154, v156, v154, s[6:7]
	v_cndmask_b32_e64 v177, v157, v155, s[8:9]
	v_cndmask_b32_e64 v155, v157, v155, s[6:7]
	v_mov_b32_dpp v154, v154 row_ror:2 row_mask:0xf bank_mask:0xf
	s_nop 1
	v_mov_b32_dpp v155, v155 row_ror:2 row_mask:0xf bank_mask:0xf
	v_mov_b32_dpp v211, v177 row_ror:1 row_mask:0xf bank_mask:0xf
	s_waitcnt lgkmcnt(1)
	v_pk_fma_f32 v[154:155], v[130:131], v[154:155], v[142:143]
	s_waitcnt lgkmcnt(0)
	v_pk_fma_f32 v[154:155], v[134:135], v[210:211], v[154:155]
	s_nop 0
	v_pk_fma_f32 v[154:155], v[156:157], v[138:139], v[154:155]
	s_nop 0
	v_mul_f32_e32 v177, 0xbfb8aa3b, v154
	v_exp_f32_e32 v177, v177
	s_nop 0
	v_add_f32_e32 v177, 1.0, v177
	v_rcp_f32_e32 v210, v177
	v_mul_f32_e32 v177, 0xbfb8aa3b, v155
	v_exp_f32_e32 v177, v177
	s_nop 0
	v_add_f32_e32 v177, 1.0, v177
	v_rcp_f32_e32 v211, v177
	v_cndmask_b32_e64 v177, v148, v152, s[8:9]
	v_cndmask_b32_e64 v152, v148, v152, s[6:7]
	s_nop 1
	v_mov_b32_dpp v152, v152 row_ror:2 row_mask:0xf bank_mask:0xf
	v_pk_mul_f32 v[154:155], v[154:155], v[210:211]
	v_pk_mul_f32 v[210:211], v[70:71], v[178:179] op_sel_hi:[1,0]
	v_pk_mul_f32 v[154:155], v[204:205], v[154:155]
	v_mov_b32_dpp v204, v177 row_ror:1 row_mask:0xf bank_mask:0xf
	v_cndmask_b32_e64 v177, v149, v153, s[8:9]
	v_cndmask_b32_e64 v153, v149, v153, s[6:7]
	s_nop 1
	v_mov_b32_dpp v153, v153 row_ror:2 row_mask:0xf bank_mask:0xf
	v_mov_b32_dpp v205, v177 row_ror:1 row_mask:0xf bank_mask:0xf
	v_cvt_pk_bf16_f32 v154, v154, v155
	s_waitcnt lgkmcnt(1)
	v_pk_fma_f32 v[152:153], v[132:133], v[152:153], v[144:145]
	s_waitcnt lgkmcnt(0)
	v_pk_fma_f32 v[152:153], v[136:137], v[204:205], v[152:153]
	s_nop 0
	v_pk_fma_f32 v[152:153], v[148:149], v[140:141], v[152:153]
	s_nop 0
	v_mul_f32_e32 v177, 0xbfb8aa3b, v152
	v_exp_f32_e32 v177, v177
	s_nop 0
	v_add_f32_e32 v177, 1.0, v177
	v_rcp_f32_e32 v204, v177
	v_mul_f32_e32 v177, 0xbfb8aa3b, v153
	v_exp_f32_e32 v177, v177
	s_nop 0
	v_add_f32_e32 v177, 1.0, v177
	v_rcp_f32_e32 v205, v177
	s_nop 0
	v_pk_mul_f32 v[152:153], v[152:153], v[204:205]
	s_nop 0
	v_pk_mul_f32 v[152:153], v[202:203], v[152:153]
	v_pk_mul_f32 v[204:205], v[72:73], v[178:179] op_sel_hi:[1,0]
	v_cvt_pk_bf16_f32 v155, v152, v153
	v_mad_i64_i32 v[152:153], s[20:21], v188, s47, v[146:147]
	v_lshl_add_u64 v[202:203], v[152:153], 0, v[150:151]
	global_store_dwordx2 v[202:203], v[154:155], off
	v_pk_mul_f32 v[154:155], v[102:103], v[178:179] op_sel_hi:[1,0]
	v_pk_mul_f32 v[152:153], v[104:105], v[178:179] op_sel_hi:[1,0]
	v_cndmask_b32_e64 v177, v154, v156, s[8:9]
	s_nop 1
	v_mov_b32_dpp v212, v177 row_ror:1 row_mask:0xf bank_mask:0xf
	v_cndmask_b32_e64 v156, v154, v156, s[6:7]
	v_cndmask_b32_e64 v177, v155, v157, s[8:9]
	v_cndmask_b32_e64 v157, v155, v157, s[6:7]
	v_mov_b32_dpp v156, v156 row_ror:2 row_mask:0xf bank_mask:0xf
	s_nop 1
	v_mov_b32_dpp v157, v157 row_ror:2 row_mask:0xf bank_mask:0xf
	v_mov_b32_dpp v213, v177 row_ror:1 row_mask:0xf bank_mask:0xf
	v_mad_i64_i32 v[146:147], s[20:21], v186, s47, v[146:147]
	s_waitcnt lgkmcnt(1)
; #define PG8_LAS __attribute__((address_space(3)))
; __device__ __forceinline__ unsigned cvt_pk_bf16(float lo, float hi) { f32x2_t v = {lo, hi}; bf16x2_t b = __builtin_convertvector(v, bf16x2_t); return __builtin_bit_cast(unsigned, b); }
; __device__ __forceinline__ float sigm(float x) { return __builtin_amdgcn_rcpf(1.0f + __builtin_amdgcn_exp2f(-x * LOG2E)); }
;     __device__ __forceinline__ void operator()(const f32x4 (&acc)[2][2][4][2], const Unit& u, int wr, int wc, int fr, int fq) const {
;     ...
;                     if (has_prev && fr >= 14) { const int pw = (wr == 1 ? 0 : 4) + wc, pai = (wr == 1) ? ai : 0; prevA = *(const PG8_LAS f32x4*)(xch + ((pw * 8 + (fr - 14) * 4 + fq) * 16 + pai * 8 + n * 4)); }
;     ...
; #pragma unroll
;                     for (int m = 0; m < 4; ++m) {
;                         const int row = row0 + ai * HALF + m * 16;
;                         const f32x4 a = acc[ai][0][m][n] * rs[ai][m], uu = acc[ai][1][m][n] * rs[ai][m]; f32x4 gg;
; #pragma unroll
;                         for (int j = 0; j < 4; ++j) {
;                             const float p1 = __builtin_bit_cast(float, __builtin_amdgcn_ds_bpermute(idx1, __builtin_bit_cast(int, fr == 15 ? prevA[j] : a[j])));
;                             const float p2 = __builtin_bit_cast(float, __builtin_amdgcn_ds_bpermute(idx2, __builtin_bit_cast(int, fr >= 14 ? prevA[j] : a[j])));
;                             const float c = bb[j] + w0[j] * p2 + w1[j] * p1 + w2[j] * a[j];
;                             gg[j] = c * sigm(c) * uu[j];
;                         }
;                         *(u32x2*)(G + (size_t)row * 2816 + colt + 4 * n) = (u32x2){cvt_pk_bf16(gg[0], gg[1]), cvt_pk_bf16(gg[2], gg[3])};
	v_pk_fma_f32 v[156:157], v[130:131], v[156:157], v[142:143]
	s_waitcnt lgkmcnt(0)
	v_pk_fma_f32 v[156:157], v[134:135], v[212:213], v[156:157]
	s_nop 0
	v_pk_fma_f32 v[154:155], v[154:155], v[138:139], v[156:157]
	s_nop 0
	v_mul_f32_e32 v156, 0xbfb8aa3b, v154
	v_mul_f32_e32 v157, 0xbfb8aa3b, v155
	v_exp_f32_e32 v156, v156
	v_exp_f32_e32 v157, v157
	v_add_f32_e32 v156, 1.0, v156
	v_add_f32_e32 v157, 1.0, v157
	v_rcp_f32_e32 v156, v156
	v_rcp_f32_e32 v157, v157
	s_nop 0
	v_pk_mul_f32 v[154:155], v[154:155], v[156:157]
	v_cndmask_b32_e64 v156, v152, v148, s[8:9]
	v_cndmask_b32_e64 v148, v152, v148, s[6:7]
	v_cndmask_b32_e64 v157, v153, v149, s[8:9]
	v_cndmask_b32_e64 v149, v153, v149, s[6:7]
	v_mov_b32_dpp v148, v148 row_ror:2 row_mask:0xf bank_mask:0xf
	s_nop 1
	v_mov_b32_dpp v149, v149 row_ror:2 row_mask:0xf bank_mask:0xf
	v_mov_b32_dpp v156, v156 row_ror:1 row_mask:0xf bank_mask:0xf
	v_mov_b32_dpp v157, v157 row_ror:1 row_mask:0xf bank_mask:0xf
	v_pk_mul_f32 v[154:155], v[210:211], v[154:155]
	s_waitcnt lgkmcnt(2)
	v_pk_fma_f32 v[148:149], v[132:133], v[148:149], v[144:145]
	s_waitcnt lgkmcnt(0)
	v_pk_fma_f32 v[148:149], v[136:137], v[156:157], v[148:149]
	s_nop 0
	v_pk_fma_f32 v[148:149], v[152:153], v[140:141], v[148:149]
	s_nop 0
	v_mul_f32_e32 v152, 0xbfb8aa3b, v148
	v_mul_f32_e32 v153, 0xbfb8aa3b, v149
	v_exp_f32_e32 v152, v152
	v_exp_f32_e32 v153, v153
	v_add_f32_e32 v152, 1.0, v152
	v_add_f32_e32 v153, 1.0, v153
	v_rcp_f32_e32 v152, v152
	v_rcp_f32_e32 v153, v153
	s_nop 0
	v_pk_mul_f32 v[148:149], v[148:149], v[152:153]
	s_nop 0
	v_pk_mul_f32 v[148:149], v[204:205], v[148:149]
	v_cvt_pk_bf16_f32 v152, v154, v155
	v_cvt_pk_bf16_f32 v153, v148, v149
	v_lshl_add_u64 v[204:205], v[146:147], 0, v[150:151]
	v_mov_b32_e32 v146, 0
	v_mov_b32_e32 v147, 0
	v_mov_b32_e32 v148, 0
	v_mov_b32_e32 v149, 0
	global_store_dwordx2 v[204:205], v[152:153], off
	s_and_saveexec_b64 s[90:91], s[6:7]
	s_cbranch_execz .LBB0_1004
	v_readlane_b32 s20, v255, 15
	s_lshl_b32 s20, s20, 2
	s_nop 0
	v_add3_u32 v146, v173, v171, s20
	v_add_u32_e32 v146, 0xfffff200, v146
	ds_read_b128 v[146:149], v146
.LBB0_1004:
	s_or_b64 exec, exec, s[90:91]
	v_pk_mul_f32 v[156:157], v[62:63], v[176:177] op_sel_hi:[1,0]
	v_pk_mul_f32 v[154:155], v[64:65], v[176:177] op_sel_hi:[1,0]
	v_pk_mul_f32 v[152:153], v[32:33], v[176:177] op_sel_hi:[1,0]
	v_pk_mul_f32 v[212:213], v[30:31], v[176:177] op_sel_hi:[1,0]
	s_waitcnt lgkmcnt(0)
	v_cndmask_b32_e64 v177, v156, v146, s[8:9]
	s_nop 1
	v_mov_b32_dpp v214, v177 row_ror:1 row_mask:0xf bank_mask:0xf
	v_cndmask_b32_e64 v146, v156, v146, s[6:7]
	v_cndmask_b32_e64 v177, v157, v147, s[8:9]
	v_cndmask_b32_e64 v147, v157, v147, s[6:7]
	v_mov_b32_dpp v146, v146 row_ror:2 row_mask:0xf bank_mask:0xf
	s_nop 1
	v_mov_b32_dpp v147, v147 row_ror:2 row_mask:0xf bank_mask:0xf
	v_mov_b32_dpp v215, v177 row_ror:1 row_mask:0xf bank_mask:0xf
	v_add_u32_e32 v210, -14, v237
	v_lshl_add_u32 v211, s34, 1, v210
	s_waitcnt lgkmcnt(1)
	v_pk_fma_f32 v[146:147], v[130:131], v[146:147], v[142:143]
	s_waitcnt lgkmcnt(0)
	v_pk_fma_f32 v[146:147], v[134:135], v[214:215], v[146:147]
	s_nop 0
	v_pk_fma_f32 v[146:147], v[156:157], v[138:139], v[146:147]
	s_nop 0
	v_mul_f32_e32 v177, 0xbfb8aa3b, v146
	v_exp_f32_e32 v177, v177
	s_nop 0
	v_add_f32_e32 v177, 1.0, v177
	v_rcp_f32_e32 v214, v177
	v_mul_f32_e32 v177, 0xbfb8aa3b, v147
	v_exp_f32_e32 v177, v177
	s_nop 0
	v_add_f32_e32 v177, 1.0, v177
	v_rcp_f32_e32 v215, v177
	v_cndmask_b32_e64 v177, v154, v148, s[8:9]
	v_cndmask_b32_e64 v148, v154, v148, s[6:7]
	s_nop 1
	v_mov_b32_dpp v148, v148 row_ror:2 row_mask:0xf bank_mask:0xf
	v_pk_mul_f32 v[146:147], v[146:147], v[214:215]
	v_pk_mul_f32 v[214:215], v[22:23], v[174:175] op_sel_hi:[1,0]
	v_pk_mul_f32 v[146:147], v[212:213], v[146:147]
	v_mov_b32_dpp v212, v177 row_ror:1 row_mask:0xf bank_mask:0xf
	v_cndmask_b32_e64 v177, v155, v149, s[8:9]
	v_cndmask_b32_e64 v149, v155, v149, s[6:7]
	s_nop 1
	v_mov_b32_dpp v149, v149 row_ror:2 row_mask:0xf bank_mask:0xf
	v_mov_b32_dpp v213, v177 row_ror:1 row_mask:0xf bank_mask:0xf
	v_cvt_pk_bf16_f32 v146, v146, v147
	s_waitcnt lgkmcnt(1)
	v_pk_fma_f32 v[148:149], v[132:133], v[148:149], v[144:145]
	s_waitcnt lgkmcnt(0)
	v_pk_fma_f32 v[148:149], v[136:137], v[212:213], v[148:149]
	s_nop 0
	v_pk_fma_f32 v[148:149], v[154:155], v[140:141], v[148:149]
	s_nop 0
	v_mul_f32_e32 v177, 0xbfb8aa3b, v148
	v_exp_f32_e32 v177, v177
	s_nop 0
	v_add_f32_e32 v177, 1.0, v177
	v_rcp_f32_e32 v212, v177
	v_mul_f32_e32 v177, 0xbfb8aa3b, v149
	v_exp_f32_e32 v177, v177
	s_nop 0
	v_add_f32_e32 v177, 1.0, v177
	v_rcp_f32_e32 v213, v177
	s_nop 0
	v_pk_mul_f32 v[148:149], v[148:149], v[212:213]
	s_nop 0
	v_pk_mul_f32 v[148:149], v[152:153], v[148:149]
	v_mov_b64_e32 v[152:153], s[42:43]
	v_cvt_pk_bf16_f32 v147, v148, v149
	v_mad_i64_i32 v[148:149], s[20:21], v189, s47, v[152:153]
	v_lshl_add_u64 v[188:189], v[148:149], 0, v[150:151]
	v_pk_mul_f32 v[148:149], v[54:55], v[174:175] op_sel_hi:[1,0]
	global_store_dwordx2 v[188:189], v[146:147], off
	v_cndmask_b32_e64 v177, v148, v156, s[8:9]
	s_nop 1
	v_mov_b32_dpp v216, v177 row_ror:1 row_mask:0xf bank_mask:0xf
	v_cndmask_b32_e64 v156, v148, v156, s[6:7]
	v_cndmask_b32_e64 v177, v149, v157, s[8:9]
	v_cndmask_b32_e64 v157, v149, v157, s[6:7]
	v_mov_b32_dpp v156, v156 row_ror:2 row_mask:0xf bank_mask:0xf
	s_nop 1
	v_mov_b32_dpp v157, v157 row_ror:2 row_mask:0xf bank_mask:0xf
	v_mov_b32_dpp v217, v177 row_ror:1 row_mask:0xf bank_mask:0xf
	v_pk_mul_f32 v[146:147], v[56:57], v[174:175] op_sel_hi:[1,0]
	v_pk_mul_f32 v[212:213], v[24:25], v[174:175] op_sel_hi:[1,0]
	s_waitcnt lgkmcnt(1)
; __device__ __forceinline__ unsigned cvt_pk_bf16(float lo, float hi) { f32x2_t v = {lo, hi}; bf16x2_t b = __builtin_convertvector(v, bf16x2_t); return __builtin_bit_cast(unsigned, b); }
; __device__ __forceinline__ float sigm(float x) { return __builtin_amdgcn_rcpf(1.0f + __builtin_amdgcn_exp2f(-x * LOG2E)); }
;     __device__ __forceinline__ void operator()(const f32x4 (&acc)[2][2][4][2], const Unit& u, int wr, int wc, int fr, int fq) const {
;     ...
;                     for (int m = 0; m < 4; ++m) {
;                         const int row = row0 + ai * HALF + m * 16;
;                         const f32x4 a = acc[ai][0][m][n] * rs[ai][m], uu = acc[ai][1][m][n] * rs[ai][m]; f32x4 gg;
; #pragma unroll
;                         for (int j = 0; j < 4; ++j) {
;                             const float p1 = __builtin_bit_cast(float, __builtin_amdgcn_ds_bpermute(idx1, __builtin_bit_cast(int, fr == 15 ? prevA[j] : a[j])));
;                             const float p2 = __builtin_bit_cast(float, __builtin_amdgcn_ds_bpermute(idx2, __builtin_bit_cast(int, fr >= 14 ? prevA[j] : a[j])));
;                             const float c = bb[j] + w0[j] * p2 + w1[j] * p1 + w2[j] * a[j];
;                             gg[j] = c * sigm(c) * uu[j];
;                         }
;                         *(u32x2*)(G + (size_t)row * 2816 + colt + 4 * n) = (u32x2){cvt_pk_bf16(gg[0], gg[1]), cvt_pk_bf16(gg[2], gg[3])};
	v_pk_fma_f32 v[156:157], v[130:131], v[156:157], v[142:143]
	s_waitcnt lgkmcnt(0)
	v_pk_fma_f32 v[156:157], v[134:135], v[216:217], v[156:157]
	s_nop 0
	v_pk_fma_f32 v[156:157], v[148:149], v[138:139], v[156:157]
	s_nop 0
	v_mul_f32_e32 v177, 0xbfb8aa3b, v156
	v_exp_f32_e32 v177, v177
	s_nop 0
	v_add_f32_e32 v177, 1.0, v177
	v_rcp_f32_e32 v216, v177
	v_mul_f32_e32 v177, 0xbfb8aa3b, v157
	v_exp_f32_e32 v177, v177
	s_nop 0
	v_add_f32_e32 v177, 1.0, v177
	v_rcp_f32_e32 v217, v177
	v_cndmask_b32_e64 v177, v146, v154, s[8:9]
	v_cndmask_b32_e64 v154, v146, v154, s[6:7]
	s_nop 1
	v_mov_b32_dpp v154, v154 row_ror:2 row_mask:0xf bank_mask:0xf
	v_pk_mul_f32 v[156:157], v[156:157], v[216:217]
	s_nop 0
	v_pk_mul_f32 v[156:157], v[214:215], v[156:157]
	v_mov_b32_dpp v214, v177 row_ror:1 row_mask:0xf bank_mask:0xf
	v_cndmask_b32_e64 v177, v147, v155, s[8:9]
	v_cndmask_b32_e64 v155, v147, v155, s[6:7]
	s_nop 1
	v_mov_b32_dpp v155, v155 row_ror:2 row_mask:0xf bank_mask:0xf
	v_mov_b32_dpp v215, v177 row_ror:1 row_mask:0xf bank_mask:0xf
	v_cvt_pk_bf16_f32 v156, v156, v157
	s_waitcnt lgkmcnt(1)
	v_pk_fma_f32 v[154:155], v[132:133], v[154:155], v[144:145]
	s_waitcnt lgkmcnt(0)
	v_pk_fma_f32 v[154:155], v[136:137], v[214:215], v[154:155]
	s_nop 0
	v_pk_fma_f32 v[154:155], v[146:147], v[140:141], v[154:155]
	s_nop 0
	v_mul_f32_e32 v177, 0xbfb8aa3b, v154
	v_exp_f32_e32 v177, v177
	s_nop 0
	v_add_f32_e32 v177, 1.0, v177
	v_rcp_f32_e32 v214, v177
	v_mul_f32_e32 v177, 0xbfb8aa3b, v155
	v_exp_f32_e32 v177, v177
	s_nop 0
	v_add_f32_e32 v177, 1.0, v177
	v_rcp_f32_e32 v215, v177
	s_nop 0
	v_pk_mul_f32 v[154:155], v[154:155], v[214:215]
	s_nop 0
	v_pk_mul_f32 v[154:155], v[212:213], v[154:155]
	v_pk_mul_f32 v[214:215], v[14:15], v[172:173] op_sel_hi:[1,0]
	v_cvt_pk_bf16_f32 v157, v154, v155
	v_mad_i64_i32 v[154:155], s[20:21], v191, s47, v[152:153]
	v_lshl_add_u64 v[190:191], v[154:155], 0, v[150:151]
	global_store_dwordx2 v[190:191], v[156:157], off
	v_pk_mul_f32 v[156:157], v[46:47], v[172:173] op_sel_hi:[1,0]
	v_pk_mul_f32 v[154:155], v[48:49], v[172:173] op_sel_hi:[1,0]
	v_cndmask_b32_e64 v177, v156, v148, s[8:9]
	s_nop 1
	v_mov_b32_dpp v216, v177 row_ror:1 row_mask:0xf bank_mask:0xf
	v_cndmask_b32_e64 v148, v156, v148, s[6:7]
	v_cndmask_b32_e64 v177, v157, v149, s[8:9]
	v_cndmask_b32_e64 v149, v157, v149, s[6:7]
	v_mov_b32_dpp v148, v148 row_ror:2 row_mask:0xf bank_mask:0xf
	s_nop 1
	v_mov_b32_dpp v149, v149 row_ror:2 row_mask:0xf bank_mask:0xf
	v_mov_b32_dpp v217, v177 row_ror:1 row_mask:0xf bank_mask:0xf
	v_pk_mul_f32 v[212:213], v[16:17], v[172:173] op_sel_hi:[1,0]
	s_waitcnt lgkmcnt(1)
	v_pk_fma_f32 v[148:149], v[130:131], v[148:149], v[142:143]
	s_waitcnt lgkmcnt(0)
	v_pk_fma_f32 v[148:149], v[134:135], v[216:217], v[148:149]
	s_nop 0
	v_pk_fma_f32 v[148:149], v[156:157], v[138:139], v[148:149]
	s_nop 0
	v_mul_f32_e32 v177, 0xbfb8aa3b, v148
	v_exp_f32_e32 v177, v177
	s_nop 0
	v_add_f32_e32 v177, 1.0, v177
	v_rcp_f32_e32 v216, v177
	v_mul_f32_e32 v177, 0xbfb8aa3b, v149
	v_exp_f32_e32 v177, v177
	s_nop 0
	v_add_f32_e32 v177, 1.0, v177
	v_rcp_f32_e32 v217, v177
	v_cndmask_b32_e64 v177, v154, v146, s[8:9]
	v_cndmask_b32_e64 v146, v154, v146, s[6:7]
	s_nop 1
	v_mov_b32_dpp v146, v146 row_ror:2 row_mask:0xf bank_mask:0xf
	v_pk_mul_f32 v[148:149], v[148:149], v[216:217]
	s_nop 0
	v_pk_mul_f32 v[148:149], v[214:215], v[148:149]
	v_mov_b32_dpp v214, v177 row_ror:1 row_mask:0xf bank_mask:0xf
	v_cndmask_b32_e64 v177, v155, v147, s[8:9]
	v_cndmask_b32_e64 v147, v155, v147, s[6:7]
	s_nop 1
	v_mov_b32_dpp v147, v147 row_ror:2 row_mask:0xf bank_mask:0xf
	v_mov_b32_dpp v215, v177 row_ror:1 row_mask:0xf bank_mask:0xf
	v_cvt_pk_bf16_f32 v148, v148, v149
	s_waitcnt lgkmcnt(1)
	v_pk_fma_f32 v[146:147], v[132:133], v[146:147], v[144:145]
	s_waitcnt lgkmcnt(0)
	v_pk_fma_f32 v[146:147], v[136:137], v[214:215], v[146:147]
	s_nop 0
	v_pk_fma_f32 v[146:147], v[154:155], v[140:141], v[146:147]
	s_nop 0
	v_mul_f32_e32 v177, 0xbfb8aa3b, v146
	v_exp_f32_e32 v177, v177
	s_nop 0
	v_add_f32_e32 v177, 1.0, v177
	v_rcp_f32_e32 v214, v177
	v_mul_f32_e32 v177, 0xbfb8aa3b, v147
	v_exp_f32_e32 v177, v177
	s_nop 0
	v_add_f32_e32 v177, 1.0, v177
	v_rcp_f32_e32 v215, v177
	s_nop 0
	v_pk_mul_f32 v[146:147], v[146:147], v[214:215]
	s_nop 0
	v_pk_mul_f32 v[146:147], v[212:213], v[146:147]
	v_pk_mul_f32 v[212:213], v[8:9], v[170:171] op_sel_hi:[1,0]
	v_cvt_pk_bf16_f32 v149, v146, v147
	v_mad_i64_i32 v[146:147], s[20:21], v193, s47, v[152:153]
	v_lshl_add_u64 v[192:193], v[146:147], 0, v[150:151]
	v_pk_mul_f32 v[146:147], v[38:39], v[170:171] op_sel_hi:[1,0]
	global_store_dwordx2 v[192:193], v[148:149], off
	v_cndmask_b32_e64 v177, v146, v156, s[8:9]
	s_nop 1
	v_mov_b32_dpp v216, v177 row_ror:1 row_mask:0xf bank_mask:0xf
	v_cndmask_b32_e64 v156, v146, v156, s[6:7]
	v_cndmask_b32_e64 v177, v147, v157, s[8:9]
	v_cndmask_b32_e64 v157, v147, v157, s[6:7]
	v_mov_b32_dpp v156, v156 row_ror:2 row_mask:0xf bank_mask:0xf
	s_nop 1
	v_mov_b32_dpp v157, v157 row_ror:2 row_mask:0xf bank_mask:0xf
	v_mov_b32_dpp v217, v177 row_ror:1 row_mask:0xf bank_mask:0xf
	v_pk_mul_f32 v[148:149], v[40:41], v[170:171] op_sel_hi:[1,0]
	v_pk_mul_f32 v[214:215], v[6:7], v[170:171] op_sel_hi:[1,0]
	s_waitcnt lgkmcnt(1)
	v_pk_fma_f32 v[130:131], v[130:131], v[156:157], v[142:143]
	s_waitcnt lgkmcnt(0)
; #define PG8_LAS __attribute__((address_space(3)))
;     __device__ __forceinline__ void operator()(const f32x4 (&acc)[2][2][4][2], const Unit& u, int wr, int wc, int fr, int fq) const {
;     ...
;             for (int n = 0; n < 2; ++n) {
;                 const f32x4 w0 = *(const f32x4*)(cw + colt + 4 * n), w1 = *(const f32x4*)(cw + 2816 + colt + 4 * n), w2 = *(const f32x4*)(cw + 5632 + colt + 4 * n), bb = *(const f32x4*)(cb + colt + 4 * n);
; #pragma unroll
;                 for (int ai = 0; ai < 2; ++ai) {
;                     f32x4 prevA = {0.f, 0.f, 0.f, 0.f};
;                     const bool has_prev = (wr == 1) || (ai == 1);
;     ...
;                     if (has_prev && fr >= 14) { const int pw = (wr == 1 ? 0 : 4) + wc, pai = (wr == 1) ? ai : 0; prevA = *(const PG8_LAS f32x4*)(xch + ((pw * 8 + (fr - 14) * 4 + fq) * 16 + pai * 8 + n * 4)); }
;     ...
; #pragma unroll
;                     for (int m = 0; m < 4; ++m) {
;                         const int row = row0 + ai * HALF + m * 16;
;                         const f32x4 a = acc[ai][0][m][n] * rs[ai][m], uu = acc[ai][1][m][n] * rs[ai][m]; f32x4 gg;
; #pragma unroll
;                         for (int j = 0; j < 4; ++j) {
;                             const float p1 = __builtin_bit_cast(float, __builtin_amdgcn_ds_bpermute(idx1, __builtin_bit_cast(int, fr == 15 ? prevA[j] : a[j])));
;                             const float p2 = __builtin_bit_cast(float, __builtin_amdgcn_ds_bpermute(idx2, __builtin_bit_cast(int, fr >= 14 ? prevA[j] : a[j])));
;                             const float c = bb[j] + w0[j] * p2 + w1[j] * p1 + w2[j] * a[j];
;                             gg[j] = c * sigm(c) * uu[j];
;                         }
;                         *(u32x2*)(G + (size_t)row * 2816 + colt + 4 * n) = (u32x2){cvt_pk_bf16(gg[0], gg[1]), cvt_pk_bf16(gg[2], gg[3])};
;                         if (ai == 0 && m == 0 && wr == 0 && fr < 2) { *(f32x4*)(HALO_A + (size_t)(u.pm * 2 + fr) * 2816 + colt + 4 * n) = a; *(f32x4*)(HALO_U + (size_t)(u.pm * 2 + fr) * 2816 + colt + 4 * n) = uu; }
;                         if (ai == 1 && m == 3 && wr == 1 && fr >= 14) { *(f32x4*)(LASTA + (size_t)(u.pm * 2 + fr - 14) * 2816 + colt + 4 * n) = a;
;                             if ((u.pm & 31) == 31) *(f32x4*)(ocp + (size_t)((u.pm >> 5) * 2 + fr - 14) * 2816 + colt + 4 * n) = a; }
	v_pk_fma_f32 v[130:131], v[134:135], v[216:217], v[130:131]
	s_nop 0
	v_pk_fma_f32 v[130:131], v[146:147], v[138:139], v[130:131]
	v_cndmask_b32_e64 v139, v149, v155, s[6:7]
	v_mul_f32_e32 v134, 0xbfb8aa3b, v130
	v_mul_f32_e32 v135, 0xbfb8aa3b, v131
	v_exp_f32_e32 v134, v134
	v_exp_f32_e32 v135, v135
	v_mov_b32_dpp v139, v139 row_ror:2 row_mask:0xf bank_mask:0xf
	v_add_f32_e32 v134, 1.0, v134
	v_add_f32_e32 v135, 1.0, v135
	v_rcp_f32_e32 v134, v134
	v_rcp_f32_e32 v135, v135
	s_nop 0
	v_pk_mul_f32 v[130:131], v[130:131], v[134:135]
	v_cndmask_b32_e64 v135, v148, v154, s[6:7]
	v_cndmask_b32_e64 v134, v148, v154, s[8:9]
	s_nop 1
	v_mov_b32_dpp v138, v135 row_ror:2 row_mask:0xf bank_mask:0xf
	v_cndmask_b32_e64 v135, v149, v155, s[8:9]
	v_mov_b32_dpp v134, v134 row_ror:1 row_mask:0xf bank_mask:0xf
	s_nop 1
	v_mov_b32_dpp v135, v135 row_ror:1 row_mask:0xf bank_mask:0xf
	v_pk_mul_f32 v[130:131], v[214:215], v[130:131]
	s_waitcnt lgkmcnt(2)
	v_pk_fma_f32 v[132:133], v[132:133], v[138:139], v[144:145]
	v_cvt_pk_bf16_f32 v130, v130, v131
	s_waitcnt lgkmcnt(0)
	v_pk_fma_f32 v[132:133], v[136:137], v[134:135], v[132:133]
	s_nop 0
	v_pk_fma_f32 v[132:133], v[148:149], v[140:141], v[132:133]
	s_nop 0
	v_mul_f32_e32 v134, 0xbfb8aa3b, v132
	v_mul_f32_e32 v135, 0xbfb8aa3b, v133
	v_exp_f32_e32 v134, v134
	v_exp_f32_e32 v135, v135
	v_add_f32_e32 v134, 1.0, v134
	v_add_f32_e32 v135, 1.0, v135
	v_rcp_f32_e32 v134, v134
	v_rcp_f32_e32 v135, v135
	s_nop 0
	v_pk_mul_f32 v[132:133], v[132:133], v[134:135]
	s_nop 0
	v_pk_mul_f32 v[132:133], v[212:213], v[132:133]
	s_nop 0
	v_cvt_pk_bf16_f32 v131, v132, v133
	v_mad_i64_i32 v[132:133], s[20:21], v187, s47, v[152:153]
	v_lshl_add_u64 v[186:187], v[132:133], 0, v[150:151]
	global_store_dwordx2 v[186:187], v[130:131], off
	s_and_saveexec_b64 s[90:91], s[12:13]
	s_cbranch_execz .LBB0_1007
	v_readlane_b32 s20, v255, 20
	v_readlane_b32 s21, v255, 21
	s_nop 1
	v_mov_b64_e32 v[130:131], s[20:21]
	v_mad_i64_i32 v[130:131], s[20:21], v211, s48, v[130:131]
	s_and_b32 s20, s34, 31
	v_lshl_add_u64 v[130:131], v[168:169], 2, v[130:131]
	s_cmp_lg_u32 s20, 31
	global_store_dwordx4 v[130:131], v[146:149], off
	s_cbranch_scc1 .LBB0_1007
	s_ashr_i32 s20, s34, 4
	s_and_b32 s20, s20, -2
	v_add_u32_e32 v132, s20, v210
	v_readlane_b32 s20, v255, 22
	v_readlane_b32 s21, v255, 23
	s_nop 1
	v_mov_b64_e32 v[130:131], s[20:21]
	v_mad_i64_i32 v[130:131], s[20:21], v132, s48, v[130:131]
	v_lshl_add_u64 v[130:131], v[168:169], 2, v[130:131]
	global_store_dwordx4 v[130:131], v[146:149], off
.LBB0_1007:
	s_or_b64 exec, exec, s[90:91]
	v_mov_b32_e32 v154, 0
	v_mov_b32_e32 v155, 0
	v_mov_b32_e32 v156, 0
	v_mov_b32_e32 v157, 0
	s_and_saveexec_b64 s[90:91], s[12:13]
	s_movk_i32 s20, 0xf210
	v_add3_u32 v146, v173, v171, s20
	ds_read_b128 v[154:157], v146
	s_or_b64 exec, exec, s[90:91]
	v_mov_b32_e32 v185, v184
	v_pk_mul_f32 v[146:147], v[122:123], v[184:185]
	v_mov_b32_e32 v150, v184
	v_mov_b32_e32 v151, v184
	s_waitcnt lgkmcnt(0)
	v_cndmask_b32_e64 v177, v146, v154, s[8:9]
	v_pk_mul_f32 v[148:149], v[124:125], v[150:151]
	v_pk_mul_f32 v[152:153], v[92:93], v[150:151]
	v_pk_mul_f32 v[150:151], v[90:91], v[184:185]
	v_mov_b32_dpp v184, v177 row_ror:1 row_mask:0xf bank_mask:0xf
	v_cndmask_b32_e64 v154, v146, v154, s[6:7]
	v_cndmask_b32_e64 v177, v147, v155, s[8:9]
	v_cndmask_b32_e64 v155, v147, v155, s[6:7]
	v_mov_b32_dpp v154, v154 row_ror:2 row_mask:0xf bank_mask:0xf
	s_nop 1
	v_mov_b32_dpp v155, v155 row_ror:2 row_mask:0xf bank_mask:0xf
	v_mov_b32_dpp v185, v177 row_ror:1 row_mask:0xf bank_mask:0xf
	s_waitcnt lgkmcnt(1)
	v_pk_fma_f32 v[154:155], v[218:219], v[154:155], v[244:245]
	s_waitcnt lgkmcnt(0)
	v_pk_fma_f32 v[154:155], v[222:223], v[184:185], v[154:155]
	s_nop 0
	v_pk_fma_f32 v[154:155], v[146:147], v[226:227], v[154:155]
	s_nop 0
	v_mul_f32_e32 v177, 0xbfb8aa3b, v154
	v_exp_f32_e32 v177, v177
	s_nop 0
	v_add_f32_e32 v177, 1.0, v177
	v_rcp_f32_e32 v184, v177
	v_mul_f32_e32 v177, 0xbfb8aa3b, v155
	v_exp_f32_e32 v177, v177
	s_nop 0
	v_add_f32_e32 v177, 1.0, v177
	v_rcp_f32_e32 v185, v177
	v_cndmask_b32_e64 v177, v148, v156, s[8:9]
	v_cndmask_b32_e64 v156, v148, v156, s[6:7]
	s_nop 1
	v_mov_b32_dpp v156, v156 row_ror:2 row_mask:0xf bank_mask:0xf
	v_pk_mul_f32 v[154:155], v[154:155], v[184:185]
	v_mov_b32_dpp v184, v177 row_ror:1 row_mask:0xf bank_mask:0xf
	v_cndmask_b32_e64 v177, v149, v157, s[8:9]
	v_cndmask_b32_e64 v157, v149, v157, s[6:7]
	s_nop 1
	v_mov_b32_dpp v157, v157 row_ror:2 row_mask:0xf bank_mask:0xf
	v_mov_b32_dpp v185, v177 row_ror:1 row_mask:0xf bank_mask:0xf
	v_pk_mul_f32 v[154:155], v[150:151], v[154:155]
	s_waitcnt lgkmcnt(1)
	v_pk_fma_f32 v[156:157], v[220:221], v[156:157], v[246:247]
	s_waitcnt lgkmcnt(0)
	v_pk_fma_f32 v[156:157], v[224:225], v[184:185], v[156:157]
	v_cvt_pk_bf16_f32 v154, v154, v155
	v_pk_fma_f32 v[156:157], v[148:149], v[228:229], v[156:157]
	s_nop 0
	v_mul_f32_e32 v177, 0xbfb8aa3b, v156
	v_exp_f32_e32 v177, v177
	s_nop 0
	v_add_f32_e32 v177, 1.0, v177
	v_rcp_f32_e32 v184, v177
	v_mul_f32_e32 v177, 0xbfb8aa3b, v157
	v_exp_f32_e32 v177, v177
	s_nop 0
	v_add_f32_e32 v177, 1.0, v177
	v_rcp_f32_e32 v185, v177
	s_nop 0
	v_pk_mul_f32 v[156:157], v[156:157], v[184:185]
	s_nop 0
	v_pk_mul_f32 v[156:157], v[152:153], v[156:157]
	s_nop 0
	v_cvt_pk_bf16_f32 v155, v156, v157
	global_store_dwordx2 v[206:207], v[154:155], off offset:8
	s_and_saveexec_b64 s[90:91], s[88:89]
	s_cbranch_execz .LBB0_1011
	v_readlane_b32 s20, v255, 16
	v_readlane_b32 s21, v255, 17
	s_nop 1
	v_mov_b64_e32 v[154:155], s[20:21]
	v_mad_i64_i32 v[154:155], s[20:21], v175, s48, v[154:155]
	v_readlane_b32 s20, v255, 18
	v_lshl_add_u64 v[154:155], v[154:155], 0, v[194:195]
	v_readlane_b32 s21, v255, 19
	global_store_dwordx4 v[154:155], v[146:149], off offset:16
	s_nop 0
	v_mov_b64_e32 v[154:155], s[20:21]
	v_mad_i64_i32 v[154:155], s[20:21], v175, s48, v[154:155]
	v_lshl_add_u64 v[154:155], v[154:155], 0, v[194:195]
	global_store_dwordx4 v[154:155], v[150:153], off offset:16
; __device__ __forceinline__ unsigned cvt_pk_bf16(float lo, float hi) { f32x2_t v = {lo, hi}; bf16x2_t b = __builtin_convertvector(v, bf16x2_t); return __builtin_bit_cast(unsigned, b); }
; __device__ __forceinline__ float sigm(float x) { return __builtin_amdgcn_rcpf(1.0f + __builtin_amdgcn_exp2f(-x * LOG2E)); }
;     __device__ __forceinline__ void operator()(const f32x4 (&acc)[2][2][4][2], const Unit& u, int wr, int wc, int fr, int fq) const {
;     ...
;                     for (int m = 0; m < 4; ++m) {
;                         const int row = row0 + ai * HALF + m * 16;
;                         const f32x4 a = acc[ai][0][m][n] * rs[ai][m], uu = acc[ai][1][m][n] * rs[ai][m]; f32x4 gg;
; #pragma unroll
;                         for (int j = 0; j < 4; ++j) {
;                             const float p1 = __builtin_bit_cast(float, __builtin_amdgcn_ds_bpermute(idx1, __builtin_bit_cast(int, fr == 15 ? prevA[j] : a[j])));
;                             const float p2 = __builtin_bit_cast(float, __builtin_amdgcn_ds_bpermute(idx2, __builtin_bit_cast(int, fr >= 14 ? prevA[j] : a[j])));
;                             const float c = bb[j] + w0[j] * p2 + w1[j] * p1 + w2[j] * a[j];
;                             gg[j] = c * sigm(c) * uu[j];
;                         }
;                         *(u32x2*)(G + (size_t)row * 2816 + colt + 4 * n) = (u32x2){cvt_pk_bf16(gg[0], gg[1]), cvt_pk_bf16(gg[2], gg[3])};
.LBB0_1011:
	s_or_b64 exec, exec, s[90:91]
	v_mov_b32_e32 v183, v182
	v_pk_mul_f32 v[154:155], v[114:115], v[182:183]
	v_mov_b32_e32 v152, v182
	v_cndmask_b32_e64 v175, v154, v146, s[8:9]
	v_mov_b32_e32 v153, v182
	v_pk_mul_f32 v[156:157], v[82:83], v[182:183]
	v_mov_b32_dpp v182, v175 row_ror:1 row_mask:0xf bank_mask:0xf
	v_cndmask_b32_e64 v146, v154, v146, s[6:7]
	v_cndmask_b32_e64 v175, v155, v147, s[8:9]
	v_cndmask_b32_e64 v147, v155, v147, s[6:7]
	v_mov_b32_dpp v146, v146 row_ror:2 row_mask:0xf bank_mask:0xf
	s_nop 1
	v_mov_b32_dpp v147, v147 row_ror:2 row_mask:0xf bank_mask:0xf
	v_mov_b32_dpp v183, v175 row_ror:1 row_mask:0xf bank_mask:0xf
	v_pk_mul_f32 v[150:151], v[116:117], v[152:153]
	v_mov_b32_e32 v181, v180
	v_pk_mul_f32 v[152:153], v[84:85], v[152:153]
	s_waitcnt lgkmcnt(1)
	v_pk_fma_f32 v[146:147], v[218:219], v[146:147], v[244:245]
	v_mov_b32_e32 v179, v178
	s_waitcnt lgkmcnt(0)
	v_pk_fma_f32 v[146:147], v[222:223], v[182:183], v[146:147]
	s_nop 0
	v_pk_fma_f32 v[146:147], v[154:155], v[226:227], v[146:147]
	s_nop 0
	v_mul_f32_e32 v175, 0xbfb8aa3b, v146
	v_exp_f32_e32 v175, v175
	s_nop 0
	v_add_f32_e32 v175, 1.0, v175
	v_rcp_f32_e32 v182, v175
	v_mul_f32_e32 v175, 0xbfb8aa3b, v147
	v_exp_f32_e32 v175, v175
	s_nop 0
	v_add_f32_e32 v175, 1.0, v175
	v_rcp_f32_e32 v183, v175
	s_nop 0
	v_pk_mul_f32 v[146:147], v[146:147], v[182:183]
	s_nop 0
	v_pk_mul_f32 v[146:147], v[156:157], v[146:147]
	v_cndmask_b32_e64 v156, v150, v148, s[8:9]
	v_cndmask_b32_e64 v148, v150, v148, s[6:7]
	v_cndmask_b32_e64 v157, v151, v149, s[8:9]
	v_cndmask_b32_e64 v149, v151, v149, s[6:7]
	v_mov_b32_dpp v148, v148 row_ror:2 row_mask:0xf bank_mask:0xf
	s_nop 1
	v_mov_b32_dpp v149, v149 row_ror:2 row_mask:0xf bank_mask:0xf
	v_mov_b32_dpp v156, v156 row_ror:1 row_mask:0xf bank_mask:0xf
	v_mov_b32_dpp v157, v157 row_ror:1 row_mask:0xf bank_mask:0xf
	v_cvt_pk_bf16_f32 v146, v146, v147
	s_waitcnt lgkmcnt(2)
	v_pk_fma_f32 v[148:149], v[220:221], v[148:149], v[246:247]
	s_waitcnt lgkmcnt(0)
	v_pk_fma_f32 v[148:149], v[224:225], v[156:157], v[148:149]
	s_nop 0
	v_pk_fma_f32 v[148:149], v[150:151], v[228:229], v[148:149]
	s_nop 0
	v_mul_f32_e32 v156, 0xbfb8aa3b, v148
	v_mul_f32_e32 v157, 0xbfb8aa3b, v149
	v_exp_f32_e32 v156, v156
	v_exp_f32_e32 v157, v157
	v_add_f32_e32 v156, 1.0, v156
	v_add_f32_e32 v157, 1.0, v157
	v_rcp_f32_e32 v156, v156
	v_rcp_f32_e32 v157, v157
	s_nop 0
	v_pk_mul_f32 v[148:149], v[148:149], v[156:157]
	s_nop 0
	v_pk_mul_f32 v[148:149], v[152:153], v[148:149]
	v_pk_mul_f32 v[152:153], v[106:107], v[180:181]
	v_cvt_pk_bf16_f32 v147, v148, v149
	v_cndmask_b32_e64 v175, v152, v154, s[8:9]
	v_mov_b32_e32 v148, v180
	v_mov_b32_e32 v149, v180
	v_pk_mul_f32 v[156:157], v[74:75], v[180:181]
	v_mov_b32_dpp v180, v175 row_ror:1 row_mask:0xf bank_mask:0xf
	v_cndmask_b32_e64 v154, v152, v154, s[6:7]
	v_cndmask_b32_e64 v175, v153, v155, s[8:9]
	v_cndmask_b32_e64 v155, v153, v155, s[6:7]
	v_mov_b32_dpp v154, v154 row_ror:2 row_mask:0xf bank_mask:0xf
	s_nop 1
	v_mov_b32_dpp v155, v155 row_ror:2 row_mask:0xf bank_mask:0xf
	v_mov_b32_dpp v181, v175 row_ror:1 row_mask:0xf bank_mask:0xf
	global_store_dwordx2 v[200:201], v[146:147], off offset:8
	v_pk_mul_f32 v[146:147], v[108:109], v[148:149]
	v_pk_mul_f32 v[148:149], v[76:77], v[148:149]
	s_waitcnt lgkmcnt(1)
	v_pk_fma_f32 v[154:155], v[218:219], v[154:155], v[244:245]
	s_waitcnt lgkmcnt(0)
	v_pk_fma_f32 v[154:155], v[222:223], v[180:181], v[154:155]
	s_nop 0
	v_pk_fma_f32 v[154:155], v[152:153], v[226:227], v[154:155]
	s_nop 0
	v_mul_f32_e32 v175, 0xbfb8aa3b, v154
	v_exp_f32_e32 v175, v175
	s_nop 0
	v_add_f32_e32 v175, 1.0, v175
	v_rcp_f32_e32 v180, v175
	v_mul_f32_e32 v175, 0xbfb8aa3b, v155
	v_exp_f32_e32 v175, v175
	s_nop 0
	v_add_f32_e32 v175, 1.0, v175
	v_rcp_f32_e32 v181, v175
	s_nop 0
	v_pk_mul_f32 v[154:155], v[154:155], v[180:181]
	s_nop 0
	v_pk_mul_f32 v[154:155], v[156:157], v[154:155]
	v_cndmask_b32_e64 v156, v146, v150, s[8:9]
	v_cndmask_b32_e64 v150, v146, v150, s[6:7]
	v_cndmask_b32_e64 v157, v147, v151, s[8:9]
	v_cndmask_b32_e64 v151, v147, v151, s[6:7]
	v_mov_b32_dpp v150, v150 row_ror:2 row_mask:0xf bank_mask:0xf
	s_nop 1
	v_mov_b32_dpp v151, v151 row_ror:2 row_mask:0xf bank_mask:0xf
	v_mov_b32_dpp v156, v156 row_ror:1 row_mask:0xf bank_mask:0xf
	v_mov_b32_dpp v157, v157 row_ror:1 row_mask:0xf bank_mask:0xf
	s_waitcnt lgkmcnt(2)
	v_pk_fma_f32 v[150:151], v[220:221], v[150:151], v[246:247]
	s_waitcnt lgkmcnt(0)
	v_pk_fma_f32 v[150:151], v[224:225], v[156:157], v[150:151]
	s_nop 0
	v_pk_fma_f32 v[150:151], v[146:147], v[228:229], v[150:151]
	s_nop 0
	v_mul_f32_e32 v156, 0xbfb8aa3b, v150
	v_mul_f32_e32 v157, 0xbfb8aa3b, v151
	v_exp_f32_e32 v156, v156
	v_exp_f32_e32 v157, v157
	v_add_f32_e32 v156, 1.0, v156
	v_add_f32_e32 v157, 1.0, v157
	v_rcp_f32_e32 v156, v156
	v_rcp_f32_e32 v157, v157
	s_nop 0
	v_pk_mul_f32 v[150:151], v[150:151], v[156:157]
	s_nop 0
	v_pk_mul_f32 v[148:149], v[148:149], v[150:151]
	v_cvt_pk_bf16_f32 v150, v154, v155
	v_pk_mul_f32 v[154:155], v[98:99], v[178:179]
	v_cvt_pk_bf16_f32 v151, v148, v149
	v_cndmask_b32_e64 v175, v154, v152, s[8:9]
	v_mov_b32_e32 v148, v178
	v_mov_b32_e32 v149, v178
	v_pk_mul_f32 v[156:157], v[66:67], v[178:179]
	v_mov_b32_dpp v178, v175 row_ror:1 row_mask:0xf bank_mask:0xf
	v_cndmask_b32_e64 v152, v154, v152, s[6:7]
	v_cndmask_b32_e64 v175, v155, v153, s[8:9]
	v_cndmask_b32_e64 v153, v155, v153, s[6:7]
	v_mov_b32_dpp v152, v152 row_ror:2 row_mask:0xf bank_mask:0xf
	s_nop 1
	v_mov_b32_dpp v153, v153 row_ror:2 row_mask:0xf bank_mask:0xf
	v_mov_b32_dpp v179, v175 row_ror:1 row_mask:0xf bank_mask:0xf
	global_store_dwordx2 v[202:203], v[150:151], off offset:8
	v_pk_mul_f32 v[150:151], v[100:101], v[148:149]
	v_pk_mul_f32 v[148:149], v[68:69], v[148:149]
	s_waitcnt lgkmcnt(1)
; #define PG8_LAS __attribute__((address_space(3)))
; __device__ __forceinline__ unsigned cvt_pk_bf16(float lo, float hi) { f32x2_t v = {lo, hi}; bf16x2_t b = __builtin_convertvector(v, bf16x2_t); return __builtin_bit_cast(unsigned, b); }
; __device__ __forceinline__ float sigm(float x) { return __builtin_amdgcn_rcpf(1.0f + __builtin_amdgcn_exp2f(-x * LOG2E)); }
;     __device__ __forceinline__ void operator()(const f32x4 (&acc)[2][2][4][2], const Unit& u, int wr, int wc, int fr, int fq) const {
;     ...
;                     if (has_prev && fr >= 14) { const int pw = (wr == 1 ? 0 : 4) + wc, pai = (wr == 1) ? ai : 0; prevA = *(const PG8_LAS f32x4*)(xch + ((pw * 8 + (fr - 14) * 4 + fq) * 16 + pai * 8 + n * 4)); }
;     ...
; #pragma unroll
;                     for (int m = 0; m < 4; ++m) {
;                         const int row = row0 + ai * HALF + m * 16;
;                         const f32x4 a = acc[ai][0][m][n] * rs[ai][m], uu = acc[ai][1][m][n] * rs[ai][m]; f32x4 gg;
; #pragma unroll
;                         for (int j = 0; j < 4; ++j) {
;                             const float p1 = __builtin_bit_cast(float, __builtin_amdgcn_ds_bpermute(idx1, __builtin_bit_cast(int, fr == 15 ? prevA[j] : a[j])));
;                             const float p2 = __builtin_bit_cast(float, __builtin_amdgcn_ds_bpermute(idx2, __builtin_bit_cast(int, fr >= 14 ? prevA[j] : a[j])));
;                             const float c = bb[j] + w0[j] * p2 + w1[j] * p1 + w2[j] * a[j];
;                             gg[j] = c * sigm(c) * uu[j];
;                         }
;                         *(u32x2*)(G + (size_t)row * 2816 + colt + 4 * n) = (u32x2){cvt_pk_bf16(gg[0], gg[1]), cvt_pk_bf16(gg[2], gg[3])};
	v_pk_fma_f32 v[152:153], v[218:219], v[152:153], v[244:245]
	s_waitcnt lgkmcnt(0)
	v_pk_fma_f32 v[152:153], v[222:223], v[178:179], v[152:153]
	s_nop 0
	v_pk_fma_f32 v[152:153], v[154:155], v[226:227], v[152:153]
	s_nop 0
	v_mul_f32_e32 v154, 0xbfb8aa3b, v152
	v_mul_f32_e32 v155, 0xbfb8aa3b, v153
	v_exp_f32_e32 v154, v154
	v_exp_f32_e32 v155, v155
	v_add_f32_e32 v154, 1.0, v154
	v_add_f32_e32 v155, 1.0, v155
	v_rcp_f32_e32 v154, v154
	v_rcp_f32_e32 v155, v155
	s_nop 0
	v_pk_mul_f32 v[152:153], v[152:153], v[154:155]
	v_cndmask_b32_e64 v154, v150, v146, s[8:9]
	v_cndmask_b32_e64 v146, v150, v146, s[6:7]
	v_cndmask_b32_e64 v155, v151, v147, s[8:9]
	v_cndmask_b32_e64 v147, v151, v147, s[6:7]
	v_mov_b32_dpp v146, v146 row_ror:2 row_mask:0xf bank_mask:0xf
	s_nop 1
	v_mov_b32_dpp v147, v147 row_ror:2 row_mask:0xf bank_mask:0xf
	v_mov_b32_dpp v154, v154 row_ror:1 row_mask:0xf bank_mask:0xf
	v_mov_b32_dpp v155, v155 row_ror:1 row_mask:0xf bank_mask:0xf
	v_pk_mul_f32 v[152:153], v[156:157], v[152:153]
	s_waitcnt lgkmcnt(2)
	v_pk_fma_f32 v[146:147], v[220:221], v[146:147], v[246:247]
	s_waitcnt lgkmcnt(0)
	v_pk_fma_f32 v[146:147], v[224:225], v[154:155], v[146:147]
	s_nop 0
	v_pk_fma_f32 v[146:147], v[150:151], v[228:229], v[146:147]
	s_nop 0
	v_mul_f32_e32 v150, 0xbfb8aa3b, v146
	v_mul_f32_e32 v151, 0xbfb8aa3b, v147
	v_exp_f32_e32 v150, v150
	v_exp_f32_e32 v151, v151
	v_add_f32_e32 v150, 1.0, v150
	v_add_f32_e32 v151, 1.0, v151
	v_rcp_f32_e32 v150, v150
	v_rcp_f32_e32 v151, v151
	s_nop 0
	v_pk_mul_f32 v[146:147], v[146:147], v[150:151]
	s_nop 0
	v_pk_mul_f32 v[146:147], v[148:149], v[146:147]
	v_cvt_pk_bf16_f32 v148, v152, v153
	v_cvt_pk_bf16_f32 v149, v146, v147
	global_store_dwordx2 v[204:205], v[148:149], off offset:8
	v_mov_b32_e32 v146, 0
	v_mov_b32_e32 v147, 0
	v_mov_b32_e32 v148, 0
	v_mov_b32_e32 v149, 0
	s_and_saveexec_b64 s[88:89], s[6:7]
	s_cbranch_execz .LBB0_1013
	v_readlane_b32 s20, v255, 15
	s_lshl_b32 s20, s20, 2
	s_nop 0
	v_add3_u32 v146, v173, v171, s20
	v_add_u32_e32 v146, 0xfffff210, v146
	ds_read_b128 v[146:149], v146
.LBB0_1013:
	s_or_b64 exec, exec, s[88:89]
	v_mov_b32_e32 v177, v176
	v_pk_mul_f32 v[154:155], v[58:59], v[176:177]
	v_mov_b32_e32 v152, v176
	v_mov_b32_e32 v153, v176
	v_pk_mul_f32 v[156:157], v[26:27], v[176:177]
	s_waitcnt lgkmcnt(0)
	v_cndmask_b32_e64 v176, v154, v146, s[8:9]
	v_cndmask_b32_e64 v146, v154, v146, s[6:7]
	v_cndmask_b32_e64 v177, v155, v147, s[8:9]
	v_cndmask_b32_e64 v147, v155, v147, s[6:7]
	v_mov_b32_dpp v146, v146 row_ror:2 row_mask:0xf bank_mask:0xf
	s_nop 1
	v_mov_b32_dpp v147, v147 row_ror:2 row_mask:0xf bank_mask:0xf
	v_mov_b32_dpp v176, v176 row_ror:1 row_mask:0xf bank_mask:0xf
	v_mov_b32_dpp v177, v177 row_ror:1 row_mask:0xf bank_mask:0xf
	v_pk_mul_f32 v[150:151], v[60:61], v[152:153]
	v_mov_b32_e32 v175, v174
	s_waitcnt lgkmcnt(2)
	v_pk_fma_f32 v[146:147], v[218:219], v[146:147], v[244:245]
	v_pk_mul_f32 v[152:153], v[28:29], v[152:153]
	s_waitcnt lgkmcnt(0)
	v_pk_fma_f32 v[146:147], v[222:223], v[176:177], v[146:147]
	v_mov_b32_e32 v173, v172
	v_pk_fma_f32 v[146:147], v[154:155], v[226:227], v[146:147]
	v_mov_b32_e32 v171, v170
	v_mul_f32_e32 v176, 0xbfb8aa3b, v146
	v_mul_f32_e32 v177, 0xbfb8aa3b, v147
	v_exp_f32_e32 v176, v176
	v_exp_f32_e32 v177, v177
	v_add_f32_e32 v176, 1.0, v176
	v_add_f32_e32 v177, 1.0, v177
	v_rcp_f32_e32 v176, v176
	v_rcp_f32_e32 v177, v177
	s_nop 0
	v_pk_mul_f32 v[146:147], v[146:147], v[176:177]
	s_nop 0
	v_pk_mul_f32 v[146:147], v[156:157], v[146:147]
	v_cndmask_b32_e64 v156, v150, v148, s[8:9]
	v_cndmask_b32_e64 v148, v150, v148, s[6:7]
	v_cndmask_b32_e64 v157, v151, v149, s[8:9]
	v_cndmask_b32_e64 v149, v151, v149, s[6:7]
	v_mov_b32_dpp v148, v148 row_ror:2 row_mask:0xf bank_mask:0xf
	s_nop 1
	v_mov_b32_dpp v149, v149 row_ror:2 row_mask:0xf bank_mask:0xf
	v_mov_b32_dpp v156, v156 row_ror:1 row_mask:0xf bank_mask:0xf
	v_mov_b32_dpp v157, v157 row_ror:1 row_mask:0xf bank_mask:0xf
	v_cvt_pk_bf16_f32 v146, v146, v147
	s_waitcnt lgkmcnt(2)
	v_pk_fma_f32 v[148:149], v[220:221], v[148:149], v[246:247]
	s_waitcnt lgkmcnt(0)
	v_pk_fma_f32 v[148:149], v[224:225], v[156:157], v[148:149]
	s_nop 0
	v_pk_fma_f32 v[148:149], v[150:151], v[228:229], v[148:149]
	s_nop 0
	v_mul_f32_e32 v156, 0xbfb8aa3b, v148
	v_mul_f32_e32 v157, 0xbfb8aa3b, v149
	v_exp_f32_e32 v156, v156
	v_exp_f32_e32 v157, v157
	v_add_f32_e32 v156, 1.0, v156
	v_add_f32_e32 v157, 1.0, v157
	v_rcp_f32_e32 v156, v156
	v_rcp_f32_e32 v157, v157
	s_nop 0
	v_pk_mul_f32 v[148:149], v[148:149], v[156:157]
	s_nop 0
	v_pk_mul_f32 v[148:149], v[152:153], v[148:149]
	v_pk_mul_f32 v[152:153], v[50:51], v[174:175]
	v_cvt_pk_bf16_f32 v147, v148, v149
	v_mov_b32_e32 v148, v174
	v_mov_b32_e32 v149, v174
	v_pk_mul_f32 v[156:157], v[18:19], v[174:175]
	v_cndmask_b32_e64 v174, v152, v154, s[8:9]
	v_cndmask_b32_e64 v154, v152, v154, s[6:7]
	v_cndmask_b32_e64 v175, v153, v155, s[8:9]
	v_cndmask_b32_e64 v155, v153, v155, s[6:7]
	v_mov_b32_dpp v154, v154 row_ror:2 row_mask:0xf bank_mask:0xf
	s_nop 1
	v_mov_b32_dpp v155, v155 row_ror:2 row_mask:0xf bank_mask:0xf
	v_mov_b32_dpp v174, v174 row_ror:1 row_mask:0xf bank_mask:0xf
	v_mov_b32_dpp v175, v175 row_ror:1 row_mask:0xf bank_mask:0xf
	global_store_dwordx2 v[188:189], v[146:147], off offset:8
	v_pk_mul_f32 v[146:147], v[52:53], v[148:149]
	s_waitcnt lgkmcnt(2)
	v_pk_fma_f32 v[154:155], v[218:219], v[154:155], v[244:245]
	v_pk_mul_f32 v[148:149], v[20:21], v[148:149]
	s_waitcnt lgkmcnt(0)
; __device__ __forceinline__ unsigned cvt_pk_bf16(float lo, float hi) { f32x2_t v = {lo, hi}; bf16x2_t b = __builtin_convertvector(v, bf16x2_t); return __builtin_bit_cast(unsigned, b); }
; __device__ __forceinline__ float sigm(float x) { return __builtin_amdgcn_rcpf(1.0f + __builtin_amdgcn_exp2f(-x * LOG2E)); }
;     __device__ __forceinline__ void operator()(const f32x4 (&acc)[2][2][4][2], const Unit& u, int wr, int wc, int fr, int fq) const {
;     ...
;                     for (int m = 0; m < 4; ++m) {
;                         const int row = row0 + ai * HALF + m * 16;
;                         const f32x4 a = acc[ai][0][m][n] * rs[ai][m], uu = acc[ai][1][m][n] * rs[ai][m]; f32x4 gg;
; #pragma unroll
;                         for (int j = 0; j < 4; ++j) {
;                             const float p1 = __builtin_bit_cast(float, __builtin_amdgcn_ds_bpermute(idx1, __builtin_bit_cast(int, fr == 15 ? prevA[j] : a[j])));
;                             const float p2 = __builtin_bit_cast(float, __builtin_amdgcn_ds_bpermute(idx2, __builtin_bit_cast(int, fr >= 14 ? prevA[j] : a[j])));
;                             const float c = bb[j] + w0[j] * p2 + w1[j] * p1 + w2[j] * a[j];
;                             gg[j] = c * sigm(c) * uu[j];
;                         }
;                         *(u32x2*)(G + (size_t)row * 2816 + colt + 4 * n) = (u32x2){cvt_pk_bf16(gg[0], gg[1]), cvt_pk_bf16(gg[2], gg[3])};
	v_pk_fma_f32 v[154:155], v[222:223], v[174:175], v[154:155]
	s_nop 0
	v_pk_fma_f32 v[154:155], v[152:153], v[226:227], v[154:155]
	s_nop 0
	v_mul_f32_e32 v174, 0xbfb8aa3b, v154
	v_mul_f32_e32 v175, 0xbfb8aa3b, v155
	v_exp_f32_e32 v174, v174
	v_exp_f32_e32 v175, v175
	v_add_f32_e32 v174, 1.0, v174
	v_add_f32_e32 v175, 1.0, v175
	v_rcp_f32_e32 v174, v174
	v_rcp_f32_e32 v175, v175
	s_nop 0
	v_pk_mul_f32 v[154:155], v[154:155], v[174:175]
	s_nop 0
	v_pk_mul_f32 v[154:155], v[156:157], v[154:155]
	v_cndmask_b32_e64 v156, v146, v150, s[8:9]
	v_cndmask_b32_e64 v150, v146, v150, s[6:7]
	v_cndmask_b32_e64 v157, v147, v151, s[8:9]
	v_cndmask_b32_e64 v151, v147, v151, s[6:7]
	v_mov_b32_dpp v150, v150 row_ror:2 row_mask:0xf bank_mask:0xf
	s_nop 1
	v_mov_b32_dpp v151, v151 row_ror:2 row_mask:0xf bank_mask:0xf
	v_mov_b32_dpp v156, v156 row_ror:1 row_mask:0xf bank_mask:0xf
	v_mov_b32_dpp v157, v157 row_ror:1 row_mask:0xf bank_mask:0xf
	s_waitcnt lgkmcnt(2)
	v_pk_fma_f32 v[150:151], v[220:221], v[150:151], v[246:247]
	s_waitcnt lgkmcnt(0)
	v_pk_fma_f32 v[150:151], v[224:225], v[156:157], v[150:151]
	s_nop 0
	v_pk_fma_f32 v[150:151], v[146:147], v[228:229], v[150:151]
	s_nop 0
	v_mul_f32_e32 v156, 0xbfb8aa3b, v150
	v_mul_f32_e32 v157, 0xbfb8aa3b, v151
	v_exp_f32_e32 v156, v156
	v_exp_f32_e32 v157, v157
	v_add_f32_e32 v156, 1.0, v156
	v_add_f32_e32 v157, 1.0, v157
	v_rcp_f32_e32 v156, v156
	v_rcp_f32_e32 v157, v157
	s_nop 0
	v_pk_mul_f32 v[150:151], v[150:151], v[156:157]
	s_nop 0
	v_pk_mul_f32 v[148:149], v[148:149], v[150:151]
	v_cvt_pk_bf16_f32 v150, v154, v155
	v_pk_mul_f32 v[154:155], v[42:43], v[172:173]
	v_cvt_pk_bf16_f32 v151, v148, v149
	v_mov_b32_e32 v148, v172
	v_mov_b32_e32 v149, v172
	v_pk_mul_f32 v[156:157], v[10:11], v[172:173]
	v_cndmask_b32_e64 v172, v154, v152, s[8:9]
	v_cndmask_b32_e64 v152, v154, v152, s[6:7]
	v_cndmask_b32_e64 v173, v155, v153, s[8:9]
	v_cndmask_b32_e64 v153, v155, v153, s[6:7]
	v_mov_b32_dpp v152, v152 row_ror:2 row_mask:0xf bank_mask:0xf
	s_nop 1
	v_mov_b32_dpp v153, v153 row_ror:2 row_mask:0xf bank_mask:0xf
	v_mov_b32_dpp v172, v172 row_ror:1 row_mask:0xf bank_mask:0xf
	v_mov_b32_dpp v173, v173 row_ror:1 row_mask:0xf bank_mask:0xf
	global_store_dwordx2 v[190:191], v[150:151], off offset:8
	v_pk_mul_f32 v[150:151], v[44:45], v[148:149]
	s_waitcnt lgkmcnt(2)
	v_pk_fma_f32 v[152:153], v[218:219], v[152:153], v[244:245]
	v_pk_mul_f32 v[148:149], v[12:13], v[148:149]
	s_waitcnt lgkmcnt(0)
	v_pk_fma_f32 v[152:153], v[222:223], v[172:173], v[152:153]
	s_nop 0
	v_pk_fma_f32 v[152:153], v[154:155], v[226:227], v[152:153]
	s_nop 0
	v_mul_f32_e32 v172, 0xbfb8aa3b, v152
	v_mul_f32_e32 v173, 0xbfb8aa3b, v153
	v_exp_f32_e32 v172, v172
	v_exp_f32_e32 v173, v173
	v_add_f32_e32 v172, 1.0, v172
	v_add_f32_e32 v173, 1.0, v173
	v_rcp_f32_e32 v172, v172
	v_rcp_f32_e32 v173, v173
	s_nop 0
	v_pk_mul_f32 v[152:153], v[152:153], v[172:173]
	s_nop 0
	v_pk_mul_f32 v[152:153], v[156:157], v[152:153]
	v_cndmask_b32_e64 v156, v150, v146, s[8:9]
	v_cndmask_b32_e64 v146, v150, v146, s[6:7]
	v_cndmask_b32_e64 v157, v151, v147, s[8:9]
	v_cndmask_b32_e64 v147, v151, v147, s[6:7]
	v_mov_b32_dpp v146, v146 row_ror:2 row_mask:0xf bank_mask:0xf
	s_nop 1
	v_mov_b32_dpp v147, v147 row_ror:2 row_mask:0xf bank_mask:0xf
	v_mov_b32_dpp v156, v156 row_ror:1 row_mask:0xf bank_mask:0xf
	v_mov_b32_dpp v157, v157 row_ror:1 row_mask:0xf bank_mask:0xf
	s_waitcnt lgkmcnt(2)
	v_pk_fma_f32 v[146:147], v[220:221], v[146:147], v[246:247]
	s_waitcnt lgkmcnt(0)
	v_pk_fma_f32 v[146:147], v[224:225], v[156:157], v[146:147]
	s_nop 0
	v_pk_fma_f32 v[146:147], v[150:151], v[228:229], v[146:147]
	s_nop 0
	v_mul_f32_e32 v156, 0xbfb8aa3b, v146
	v_mul_f32_e32 v157, 0xbfb8aa3b, v147
	v_exp_f32_e32 v156, v156
	v_exp_f32_e32 v157, v157
	v_add_f32_e32 v156, 1.0, v156
	v_add_f32_e32 v157, 1.0, v157
	v_rcp_f32_e32 v156, v156
	v_rcp_f32_e32 v157, v157
	s_nop 0
	v_pk_mul_f32 v[146:147], v[146:147], v[156:157]
	s_nop 0
	v_pk_mul_f32 v[146:147], v[148:149], v[146:147]
	v_cvt_pk_bf16_f32 v148, v152, v153
	v_cvt_pk_bf16_f32 v149, v146, v147
	v_pk_mul_f32 v[146:147], v[34:35], v[170:171]
	v_mov_b32_e32 v152, v170
	v_mov_b32_e32 v153, v170
	v_pk_mul_f32 v[156:157], v[2:3], v[170:171]
	v_cndmask_b32_e64 v170, v146, v154, s[8:9]
	v_cndmask_b32_e64 v154, v146, v154, s[6:7]
	v_cndmask_b32_e64 v171, v147, v155, s[8:9]
	v_cndmask_b32_e64 v155, v147, v155, s[6:7]
	v_mov_b32_dpp v154, v154 row_ror:2 row_mask:0xf bank_mask:0xf
	s_nop 1
	v_mov_b32_dpp v155, v155 row_ror:2 row_mask:0xf bank_mask:0xf
	v_mov_b32_dpp v170, v170 row_ror:1 row_mask:0xf bank_mask:0xf
	v_mov_b32_dpp v171, v171 row_ror:1 row_mask:0xf bank_mask:0xf
	global_store_dwordx2 v[192:193], v[148:149], off offset:8
	v_pk_mul_f32 v[148:149], v[36:37], v[152:153]
	s_waitcnt lgkmcnt(2)
	v_pk_fma_f32 v[218:219], v[218:219], v[154:155], v[244:245]
	v_pk_mul_f32 v[152:153], v[4:5], v[152:153]
	s_waitcnt lgkmcnt(0)
	v_pk_fma_f32 v[218:219], v[222:223], v[170:171], v[218:219]
	s_nop 0
	v_pk_fma_f32 v[218:219], v[146:147], v[226:227], v[218:219]
	v_cndmask_b32_e64 v227, v149, v151, s[6:7]
	v_mul_f32_e32 v222, 0xbfb8aa3b, v218
	v_mul_f32_e32 v223, 0xbfb8aa3b, v219
	v_exp_f32_e32 v222, v222
	v_exp_f32_e32 v223, v223
	v_mov_b32_dpp v227, v227 row_ror:2 row_mask:0xf bank_mask:0xf
	v_add_f32_e32 v222, 1.0, v222
	v_add_f32_e32 v223, 1.0, v223
	v_rcp_f32_e32 v222, v222
	v_rcp_f32_e32 v223, v223
	s_nop 0
	v_pk_mul_f32 v[218:219], v[218:219], v[222:223]
	v_cndmask_b32_e64 v223, v148, v150, s[6:7]
	v_cndmask_b32_e64 v222, v148, v150, s[8:9]
	s_nop 1
	v_mov_b32_dpp v226, v223 row_ror:2 row_mask:0xf bank_mask:0xf
	v_cndmask_b32_e64 v223, v149, v151, s[8:9]
	v_mov_b32_dpp v222, v222 row_ror:1 row_mask:0xf bank_mask:0xf
	s_nop 1
	v_mov_b32_dpp v223, v223 row_ror:1 row_mask:0xf bank_mask:0xf
	v_pk_mul_f32 v[218:219], v[156:157], v[218:219]
	s_waitcnt lgkmcnt(2)
	v_pk_fma_f32 v[220:221], v[220:221], v[226:227], v[246:247]
	v_cvt_pk_bf16_f32 v218, v218, v219
	s_waitcnt lgkmcnt(0)
	v_pk_fma_f32 v[220:221], v[224:225], v[222:223], v[220:221]
	s_nop 0
	v_pk_fma_f32 v[220:221], v[148:149], v[228:229], v[220:221]
	s_nop 0
	v_mul_f32_e32 v222, 0xbfb8aa3b, v220
	v_mul_f32_e32 v223, 0xbfb8aa3b, v221
	v_exp_f32_e32 v222, v222
	v_exp_f32_e32 v223, v223
	v_add_f32_e32 v222, 1.0, v222
	v_add_f32_e32 v223, 1.0, v223
	v_rcp_f32_e32 v222, v222
	v_rcp_f32_e32 v223, v223
	s_nop 0
	v_pk_mul_f32 v[220:221], v[220:221], v[222:223]
	s_nop 0
	v_pk_mul_f32 v[220:221], v[152:153], v[220:221]
	s_nop 0
	v_cvt_pk_bf16_f32 v219, v220, v221
	global_store_dwordx2 v[186:187], v[218:219], off offset:8
	s_and_saveexec_b64 s[6:7], s[12:13]
	s_cbranch_execz .LBB0_1017
;     __device__ __forceinline__ void operator()(const f32x4 (&acc)[2][2][4][2], const Unit& u, int wr, int wc, int fr, int fq) const {
;     ...
;                         if (ai == 1 && m == 3 && wr == 1 && fr >= 14) { *(f32x4*)(LASTA + (size_t)(u.pm * 2 + fr - 14) * 2816 + colt + 4 * n) = a;
;                             if ((u.pm & 31) == 31) *(f32x4*)(ocp + (size_t)((u.pm >> 5) * 2 + fr - 14) * 2816 + colt + 4 * n) = a; }
	v_readlane_b32 s8, v255, 20
	v_readlane_b32 s9, v255, 21
	s_nop 1
	v_mov_b64_e32 v[218:219], s[8:9]
	v_mad_i64_i32 v[218:219], s[8:9], v211, s48, v[218:219]
	s_and_b32 s8, s34, 31
	v_lshl_add_u64 v[218:219], v[168:169], 2, v[218:219]
	s_cmp_eq_u32 s8, 31
	s_mov_b64 s[8:9], s[10:11]
	global_store_dwordx4 v[218:219], v[146:149], off offset:16
	s_cbranch_scc0 .LBB0_1016
	s_ashr_i32 s8, s34, 4
	s_and_b32 s8, s8, -2
	v_add_u32_e32 v242, s8, v210
	s_or_b64 s[8:9], s[10:11], exec
